# third row-panel barrier: gu -> down (its A rows come from the same four workgroups); sites after LN0 / after xa already panel-local, other 9 sites 3-hop sharded grid barrier
# speedup vs baseline: 1.0196x; 1.0133x over previous
.LBB0_1156:
	s_getreg_b32 s0, hwreg(HW_REG_XCC_ID, 0, 4)
	s_and_b32 s4, s0, 15
	s_waitcnt vmcnt(0)
	s_waitcnt vmcnt(0)
	s_barrier
	s_and_saveexec_b64 s[0:1], s[52:53]
	s_add_i32 s101, s101, 1
	s_cbranch_execz .LBB0_1208
	v_readlane_b32 s98, v253, 2
	v_readlane_b32 s99, v253, 3
	s_nop 0
	s_add_u32 s98, s98, 0x7c000
	s_addc_u32 s99, s99, 0
	s_and_b32 vcc_lo, s2, 63
	s_lshl_b32 vcc_lo, vcc_lo, 8
	s_add_u32 vcc_lo, vcc_lo, 0x2000
	v_mov_b32_e32 v3, vcc_lo
	v_mov_b32_e32 v4, 1
	s_lshl_b32 vcc_hi, s101, 2
	s_waitcnt vmcnt(0) lgkmcnt(0)
	global_atomic_add v5, v3, v4, s[98:99] sc0
	s_waitcnt vmcnt(0)
	v_readfirstlane_b32 vcc_lo, v5
	s_add_i32 vcc_lo, vcc_lo, 1
	s_cmp_ge_u32 vcc_lo, vcc_hi
	s_cbranch_scc1 .Lb3_ok_10
